# attention epilogue: the 8 gate-vector loads issued early into spare registers (all vmcnt waits re-derived) instead of right before the final pass
# baseline (speedup 1.0000x reference)
.LBB0_893:
	v_mov_b32_e32 v1, v254
	v_lshlrev_b32_e32 v98, 5, v206
	v_bfe_u32 v157, v1, 5, 1
	v_and_b32_e32 v156, 31, v1
	v_lshlrev_b32_e32 v66, 9, v157
	v_mov_b32_e32 v67, v0
	v_lshl_add_u64 v[66:67], s[38:39], 0, v[66:67]
	v_lshlrev_b32_e32 v68, 4, v156
	v_mov_b32_e32 v69, v0
	v_ashrrev_i32_e32 v99, 31, v98
	v_lshl_add_u64 v[100:101], v[66:67], 0, v[68:69]
	v_lshlrev_b64 v[66:67], 10, v[98:99]
	v_lshl_add_u64 v[74:75], v[100:101], 0, v[66:67]
	global_load_dwordx4 v[66:69], v[74:75], off
	v_or_b32_e32 v70, 8, v98
	v_ashrrev_i32_e32 v71, 31, v70
	v_lshlrev_b64 v[70:71], 10, v[70:71]
	v_lshl_add_u64 v[76:77], v[100:101], 0, v[70:71]
	global_load_dwordx4 v[70:73], v[76:77], off
	global_load_dwordx4 v[102:105], v[74:75], off offset:1024
	global_load_dwordx4 v[106:109], v[76:77], off offset:1024
	global_load_dwordx4 v[110:113], v[74:75], off offset:2048
	global_load_dwordx4 v[114:117], v[76:77], off offset:2048
	global_load_dwordx4 v[118:121], v[74:75], off offset:3072
	v_and_b32_e32 v79, 64, v191
	v_xor_b32_e32 v78, 32, v191
	v_add_u32_e32 v79, 64, v79
	v_cmp_lt_i32_e32 vcc, v78, v79
	global_load_dwordx4 v[122:125], v[76:77], off offset:3072
	v_lshrrev_b32_e32 v240, 1, v254
	v_and_b32_e32 v240, 0x60, v240
	v_bfe_u32 v241, v254, 4, 2
	s_and_b32 s82, s55, 0xfff
	v_add3_u32 v240, v240, v241, s82
	v_lshl_add_u32 v240, v172, 12, v240
	v_and_b32_e32 v241, 15, v254
	v_lshlrev_b32_e32 v241, 4, v241
	v_lshl_add_u32 v240, v240, 8, v241
	v_add_u32_e32 v241, 0x1000, v240
	global_load_dwordx4 v[208:211], v240, s[22:23]
	global_load_dwordx4 v[212:215], v240, s[22:23] offset:1024
	global_load_dwordx4 v[216:219], v240, s[22:23] offset:2048
	global_load_dwordx4 v[220:223], v240, s[22:23] offset:3072
	global_load_dwordx4 v[224:227], v241, s[22:23]
	global_load_dwordx4 v[228:231], v241, s[22:23] offset:1024
	global_load_dwordx4 v[232:235], v241, s[22:23] offset:2048
	global_load_dwordx4 v[236:239], v241, s[22:23] offset:3072
	v_ashrrev_i32_e32 v158, 6, v1
	v_cndmask_b32_e32 v78, v191, v78, vcc
	v_lshlrev_b32_e32 v78, 2, v78
	ds_bpermute_b32 v78, v78, v173
	v_add_co_u32_e32 v134, vcc, s37, v74
	v_bfe_u32 v160, v1, 4, 2
	s_nop 0
	v_addc_co_u32_e32 v135, vcc, 0, v75, vcc
	s_waitcnt lgkmcnt(0)
	v_add_f32_e32 v74, v173, v78
	v_div_scale_f32 v75, s[8:9], v74, v74, 1.0
	v_add_co_u32_e32 v136, vcc, s37, v76
	global_load_dwordx4 v[126:129], v[134:135], off
	v_rcp_f32_e32 v76, v75
	v_addc_co_u32_e32 v137, vcc, 0, v77, vcc
	v_div_scale_f32 v77, vcc, 1.0, v74, 1.0
	v_fma_f32 v78, -v75, v76, 1.0
	v_fmac_f32_e32 v76, v78, v76
	v_mul_f32_e32 v78, v77, v76
	v_fma_f32 v79, -v75, v78, v77
	v_fmac_f32_e32 v78, v79, v76
	v_fma_f32 v75, -v75, v78, v77
	v_div_fmas_f32 v75, v75, v76, v78
	v_div_fixup_f32 v138, v75, v74, 1.0
	v_pk_mul_f32 v[50:51], v[50:51], v[138:139] op_sel_hi:[1,0]
	v_pk_mul_f32 v[52:53], v[52:53], v[138:139] op_sel_hi:[1,0]
	v_pk_mul_f32 v[54:55], v[54:55], v[138:139] op_sel_hi:[1,0]
	v_pk_mul_f32 v[56:57], v[56:57], v[138:139] op_sel_hi:[1,0]
	v_cvt_pk_bf16_f32 v50, v50, v51
	v_cvt_pk_bf16_f32 v51, v52, v53
	v_cvt_pk_bf16_f32 v52, v54, v55
	v_cvt_pk_bf16_f32 v53, v56, v57
	global_load_dwordx4 v[54:57], v[136:137], off
	global_load_dwordx4 v[130:133], v[134:135], off offset:1024
	v_pk_mul_f32 v[58:59], v[58:59], v[138:139] op_sel_hi:[1,0]
	v_pk_mul_f32 v[60:61], v[60:61], v[138:139] op_sel_hi:[1,0]
	v_pk_mul_f32 v[62:63], v[62:63], v[138:139] op_sel_hi:[1,0]
	v_pk_mul_f32 v[64:65], v[64:65], v[138:139] op_sel_hi:[1,0]
	v_cvt_pk_bf16_f32 v58, v58, v59
	v_cvt_pk_bf16_f32 v59, v60, v61
	v_cvt_pk_bf16_f32 v60, v62, v63
	v_cvt_pk_bf16_f32 v61, v64, v65
	v_pk_mul_f32 v[34:35], v[34:35], v[138:139] op_sel_hi:[1,0]
	v_pk_mul_f32 v[36:37], v[36:37], v[138:139] op_sel_hi:[1,0]
	v_pk_mul_f32 v[38:39], v[38:39], v[138:139] op_sel_hi:[1,0]
	v_pk_mul_f32 v[40:41], v[40:41], v[138:139] op_sel_hi:[1,0]
	v_pk_mul_f32 v[42:43], v[42:43], v[138:139] op_sel_hi:[1,0]
	v_pk_mul_f32 v[44:45], v[44:45], v[138:139] op_sel_hi:[1,0]
	v_pk_mul_f32 v[46:47], v[46:47], v[138:139] op_sel_hi:[1,0]
	v_pk_mul_f32 v[48:49], v[48:49], v[138:139] op_sel_hi:[1,0]
	v_pk_mul_f32 v[18:19], v[18:19], v[138:139] op_sel_hi:[1,0]
	v_pk_mul_f32 v[20:21], v[20:21], v[138:139] op_sel_hi:[1,0]
	v_pk_mul_f32 v[22:23], v[22:23], v[138:139] op_sel_hi:[1,0]
	v_pk_mul_f32 v[24:25], v[24:25], v[138:139] op_sel_hi:[1,0]
	v_pk_mul_f32 v[26:27], v[26:27], v[138:139] op_sel_hi:[1,0]
	v_pk_mul_f32 v[28:29], v[28:29], v[138:139] op_sel_hi:[1,0]
	v_pk_mul_f32 v[30:31], v[30:31], v[138:139] op_sel_hi:[1,0]
	v_pk_mul_f32 v[32:33], v[32:33], v[138:139] op_sel_hi:[1,0]
	v_pk_mul_f32 v[2:3], v[2:3], v[138:139] op_sel_hi:[1,0]
	v_pk_mul_f32 v[4:5], v[4:5], v[138:139] op_sel_hi:[1,0]
	s_waitcnt vmcnt(18)
	v_mfma_f32_32x32x16_bf16 v[82:97], v[66:69], v[50:53], 0
	v_mul_f32_e64 v6, v6, v138
	v_mul_f32_e64 v7, v7, v138
	v_mul_f32_e64 v8, v8, v138
	v_mul_f32_e64 v9, v9, v138
	v_mul_f32_e64 v10, v10, v138
	v_mul_f32_e64 v11, v11, v138
	v_ashrrev_i32_e32 v173, 31, v172
	v_lshlrev_b32_e32 v1, 4, v1
	v_and_b32_e32 v154, 0xf0, v1
	v_mov_b32_e32 v155, v0
	s_waitcnt vmcnt(17)
	v_mfma_f32_32x32x16_bf16 v[66:81], v[70:73], v[50:53], 0
	v_mul_lo_u32 v1, v158, s45
	v_add_u32_e32 v1, 0, v1
	s_mov_b32 s14, 0
	s_waitcnt vmcnt(16)
	v_mfma_f32_32x32x16_bf16 v[82:97], v[102:105], v[58:61], v[82:97]
	global_load_dwordx4 v[62:65], v[134:135], off offset:2048
	global_load_dwordx4 v[102:105], v[134:135], off offset:3072
	s_waitcnt vmcnt(17)
	v_mfma_f32_32x32x16_bf16 v[66:81], v[106:109], v[58:61], v[66:81]
	v_cvt_pk_bf16_f32 v106, v34, v35
	v_cvt_pk_bf16_f32 v107, v36, v37
	v_cvt_pk_bf16_f32 v108, v38, v39
	v_cvt_pk_bf16_f32 v109, v40, v41
	global_load_dwordx4 v[34:37], v[136:137], off offset:1024
	global_load_dwordx4 v[38:41], v[136:137], off offset:2048
	s_waitcnt vmcnt(18)
	v_mfma_f32_32x32x16_bf16 v[82:97], v[110:113], v[106:109], v[82:97]
	v_cvt_pk_bf16_f32 v110, v42, v43
	v_cvt_pk_bf16_f32 v111, v44, v45
	global_load_dwordx4 v[42:45], v[136:137], off offset:3072
	v_cvt_pk_bf16_f32 v112, v46, v47
	v_or_b32_e32 v46, 16, v98
	v_ashrrev_i32_e32 v47, 31, v46
	v_lshlrev_b64 v[46:47], 10, v[46:47]
	v_lshl_add_u64 v[134:135], v[100:101], 0, v[46:47]
	s_waitcnt vmcnt(18)
	v_mfma_f32_32x32x16_bf16 v[66:81], v[114:117], v[106:109], v[66:81]
	v_cvt_pk_bf16_f32 v113, v48, v49
	v_cvt_pk_bf16_f32 v114, v18, v19
	v_cvt_pk_bf16_f32 v115, v20, v21
	v_cvt_pk_bf16_f32 v116, v22, v23
	v_cvt_pk_bf16_f32 v117, v24, v25
	global_load_dwordx4 v[18:21], v[134:135], off
	global_load_dwordx4 v[22:25], v[134:135], off offset:1024
	global_load_dwordx4 v[46:49], v[134:135], off offset:2048
	s_waitcnt vmcnt(20)
	v_mfma_f32_32x32x16_bf16 v[82:97], v[118:121], v[110:113], v[82:97]
	v_cvt_pk_bf16_f32 v118, v26, v27
	v_cvt_pk_bf16_f32 v119, v28, v29
	v_cvt_pk_bf16_f32 v120, v30, v31
	v_cvt_pk_bf16_f32 v121, v32, v33
	global_load_dwordx4 v[26:29], v[134:135], off offset:3072
	s_waitcnt vmcnt(20)
	v_mfma_f32_32x32x16_bf16 v[66:81], v[122:125], v[110:113], v[66:81]
	v_cvt_pk_bf16_f32 v122, v2, v3
	v_cvt_pk_bf16_f32 v123, v4, v5
	v_cvt_pk_bf16_f32 v124, v6, v7
	v_cvt_pk_bf16_f32 v125, v8, v9
	v_mul_f32_e64 v2, v12, v138
	v_mul_f32_e64 v3, v13, v138
	v_pk_mul_f32 v[4:5], v[14:15], v[138:139] op_sel_hi:[1,0]
	v_pk_mul_f32 v[6:7], v[16:17], v[138:139] op_sel_hi:[1,0]
	s_waitcnt vmcnt(11)
	v_mfma_f32_32x32x16_bf16 v[82:97], v[126:129], v[114:117], v[82:97]
	s_waitcnt vmcnt(10)
	v_mfma_f32_32x32x16_bf16 v[66:81], v[54:57], v[114:117], v[66:81]
	s_waitcnt vmcnt(9)
	v_mfma_f32_32x32x16_bf16 v[82:97], v[130:133], v[118:121], v[82:97]
	s_waitcnt vmcnt(6)
	v_mfma_f32_32x32x16_bf16 v[66:81], v[34:37], v[118:121], v[66:81]
	v_mfma_f32_32x32x16_bf16 v[82:97], v[62:65], v[122:125], v[82:97]
	v_cvt_pk_bf16_f32 v63, v2, v3
	v_add_co_u32_e32 v2, vcc, s37, v134
	v_cvt_pk_bf16_f32 v62, v10, v11
	s_nop 0
	v_addc_co_u32_e32 v3, vcc, 0, v135, vcc
	global_load_dwordx4 v[30:33], v[2:3], off
	global_load_dwordx4 v[34:37], v[2:3], off offset:1024
	s_waitcnt vmcnt(7)
	v_mfma_f32_32x32x16_bf16 v[66:81], v[38:41], v[122:125], v[66:81]
	v_cvt_pk_bf16_f32 v64, v4, v5
	v_cvt_pk_bf16_f32 v65, v6, v7
	s_waitcnt vmcnt(6)
	s_nop 0
	v_mfma_f32_32x32x16_bf16 v[66:81], v[42:45], v[62:65], v[66:81]
	global_load_dwordx4 v[38:41], v[2:3], off offset:2048
	global_load_dwordx4 v[42:45], v[2:3], off offset:3072
	s_waitcnt vmcnt(7)
	v_mfma_f32_32x32x16_bf16 v[2:17], v[18:21], v[50:53], 0
	v_or_b32_e32 v18, 24, v98
	v_ashrrev_i32_e32 v19, 31, v18
	v_lshlrev_b64 v[18:19], 10, v[18:19]
	v_lshl_add_u64 v[54:55], v[100:101], 0, v[18:19]
	global_load_dwordx4 v[18:21], v[54:55], off
	global_load_dwordx4 v[98:101], v[54:55], off offset:1024
	v_mfma_f32_32x32x16_bf16 v[82:97], v[102:105], v[62:65], v[82:97]
	global_load_dwordx4 v[102:105], v[54:55], off offset:2048
	global_load_dwordx4 v[126:129], v[54:55], off offset:3072
	s_waitcnt vmcnt(10)
	v_mfma_f32_32x32x16_bf16 v[2:17], v[22:25], v[58:61], v[2:17]
	v_add_co_u32_e32 v22, vcc, s37, v54
	v_mov_b32_e32 v24, s55
	s_nop 0
	v_addc_co_u32_e32 v23, vcc, 0, v55, vcc
	global_load_dwordx4 v[130:133], v[22:23], off
	global_load_dwordx4 v[134:137], v[22:23], off offset:1024
	global_load_dwordx4 v[138:141], v[22:23], off offset:2048
	global_load_dwordx4 v[142:145], v[22:23], off offset:3072
	s_waitcnt vmcnt(13)
	v_mfma_f32_32x32x16_bf16 v[2:17], v[46:49], v[106:109], v[2:17]
	v_lshlrev_b32_e32 v22, 5, v158
	v_and_b32_e32 v159, 0x60, v22
	v_lshlrev_b64 v[22:23], 12, v[172:173]
	v_bitop3_b32 v24, v159, s44, v24 bitop3:0xc8
	v_or3_b32 v22, v22, v24, v160
	v_lshlrev_b64 v[22:23], 8, v[22:23]
	s_waitcnt vmcnt(12)
	v_mfma_f32_32x32x16_bf16 v[2:17], v[26:29], v[110:113], v[2:17]
	s_waitcnt vmcnt(11)
	v_mfma_f32_32x32x16_bf16 v[2:17], v[30:33], v[114:117], v[2:17]
	s_waitcnt vmcnt(10)
	v_mfma_f32_32x32x16_bf16 v[2:17], v[34:37], v[118:121], v[2:17]
	v_lshl_add_u64 v[34:35], s[22:23], 0, v[22:23]
	v_lshl_add_u64 v[34:35], v[34:35], 0, v[154:155]
	s_waitcnt vmcnt(7)
	v_mfma_f32_32x32x16_bf16 v[18:33], v[18:21], v[50:53], 0
	s_waitcnt vmcnt(31)
	v_mov_b64_e32 v[146:147], v[208:209]
	v_mov_b64_e32 v[148:149], v[210:211]
	s_waitcnt vmcnt(30)
	v_mov_b64_e32 v[150:151], v[212:213]
	v_mov_b64_e32 v[152:153], v[214:215]
	s_waitcnt vmcnt(29)
	v_mov_b64_e32 v[54:55], v[216:217]
	v_mov_b64_e32 v[56:57], v[218:219]
	s_waitcnt vmcnt(28)
	v_mov_b64_e32 v[50:51], v[220:221]
	v_mov_b64_e32 v[52:53], v[222:223]
	v_add_co_u32_e32 v34, vcc, s37, v34
	s_nop 1
	v_addc_co_u32_e32 v35, vcc, 0, v35, vcc
	s_waitcnt vmcnt(6)
	v_mfma_f32_32x32x16_bf16 v[18:33], v[98:101], v[58:61], v[18:33]
	v_mul_u32_u24_e32 v98, 0x110, v156
	v_lshlrev_b32_e32 v99, 5, v157
	v_cvt_pk_f16_f32 v58, v82, v83
	v_add3_u32 v82, v1, v98, v99
	v_cvt_pk_f16_f32 v59, v84, v85
	v_cvt_pk_f16_f32 v60, v86, v87
	v_cvt_pk_f16_f32 v61, v88, v89
	s_waitcnt vmcnt(5)
	v_mfma_f32_32x32x16_bf16 v[18:33], v[102:105], v[106:109], v[18:33]
	s_waitcnt vmcnt(4)
	v_mfma_f32_32x32x16_bf16 v[18:33], v[126:129], v[110:113], v[18:33]
	s_waitcnt vmcnt(3)
	v_mfma_f32_32x32x16_bf16 v[18:33], v[130:133], v[114:117], v[18:33]
	s_waitcnt vmcnt(2)
	v_mfma_f32_32x32x16_bf16 v[18:33], v[134:137], v[118:121], v[18:33]
	v_mfma_f32_32x32x16_bf16 v[2:17], v[38:41], v[122:125], v[2:17]
	s_waitcnt vmcnt(1)
	v_mfma_f32_32x32x16_bf16 v[18:33], v[138:141], v[122:125], v[18:33]
	v_mfma_f32_32x32x16_bf16 v[2:17], v[42:45], v[62:65], v[2:17]
	s_waitcnt vmcnt(27)
	v_mov_b64_e32 v[46:47], v[224:225]
	v_mov_b64_e32 v[48:49], v[226:227]
	s_waitcnt vmcnt(26)
	v_mov_b64_e32 v[42:43], v[228:229]
	v_mov_b64_e32 v[44:45], v[230:231]
	s_waitcnt vmcnt(25)
	v_mov_b64_e32 v[38:39], v[232:233]
	v_mov_b64_e32 v[40:41], v[234:235]
	s_nop 0
	s_waitcnt vmcnt(24)
	v_mov_b64_e32 v[34:35], v[236:237]
	v_mov_b64_e32 v[36:37], v[238:239]
	ds_write_b128 v82, v[58:61] offset:49152
	v_cvt_pk_f16_f32 v58, v90, v91
	v_cvt_pk_f16_f32 v59, v92, v93
	v_cvt_pk_f16_f32 v60, v94, v95
	v_cvt_pk_f16_f32 v61, v96, v97
	ds_write_b128 v82, v[58:61] offset:49168
	s_waitcnt vmcnt(0)
	v_mfma_f32_32x32x16_bf16 v[18:33], v[142:145], v[62:65], v[18:33]
	v_cvt_pk_f16_f32 v2, v2, v3
	v_cvt_pk_f16_f32 v3, v4, v5
	v_cvt_pk_f16_f32 v4, v6, v7
	v_cvt_pk_f16_f32 v5, v8, v9
	ds_write_b128 v82, v[2:5] offset:49280
	v_cvt_pk_f16_f32 v2, v10, v11
	v_cvt_pk_f16_f32 v3, v12, v13
	v_cvt_pk_f16_f32 v4, v14, v15
	v_cvt_pk_f16_f32 v5, v16, v17
	ds_write_b128 v82, v[2:5] offset:49296
	s_nop 1
	v_cvt_pk_f16_f32 v2, v18, v19
	v_cvt_pk_f16_f32 v3, v20, v21
	v_cvt_pk_f16_f32 v4, v22, v23
	v_cvt_pk_f16_f32 v5, v24, v25
	v_cvt_pk_f16_f32 v58, v66, v67
	v_cvt_pk_f16_f32 v59, v68, v69
	v_cvt_pk_f16_f32 v60, v70, v71
	v_cvt_pk_f16_f32 v61, v72, v73
	ds_write_b128 v82, v[2:5] offset:49344
	v_cvt_pk_f16_f32 v2, v26, v27
	v_cvt_pk_f16_f32 v3, v28, v29
	v_cvt_pk_f16_f32 v4, v30, v31
	v_cvt_pk_f16_f32 v5, v32, v33
	ds_write_b128 v82, v[58:61] offset:49216
	v_cvt_pk_f16_f32 v58, v74, v75
	v_cvt_pk_f16_f32 v59, v76, v77
	v_cvt_pk_f16_f32 v60, v78, v79
	v_cvt_pk_f16_f32 v61, v80, v81
	ds_write_b128 v82, v[2:5] offset:49360
	v_mul_u32_u24_e32 v4, 0x110, v160
	ds_write_b128 v82, v[58:61] offset:49232
	v_add3_u32 v1, v1, v4, v154
	ds_read_b128 v[4:7], v1 offset:49152
	v_or3_b32 v2, v159, s55, v160
	v_mov_b32_e32 v3, v0
	v_lshlrev_b64 v[2:3], 12, v[2:3]
	v_lshlrev_b32_e32 v8, 7, v206
	v_lshl_add_u64 v[2:3], s[18:19], 0, v[2:3]
	v_ashrrev_i32_e32 v9, 31, v8
	v_lshl_add_u64 v[2:3], v[8:9], 1, v[2:3]
	ds_read_b128 v[8:11], v1 offset:50240
	s_waitcnt lgkmcnt(1)
	v_cvt_f32_f16_e32 v12, v4
	v_cvt_f32_f16_sdwa v13, v4 dst_sel:DWORD dst_unused:UNUSED_PAD src0_sel:WORD_1
	s_waitcnt vmcnt(0)
	v_lshlrev_b32_e32 v14, 16, v146
	v_and_b32_e32 v15, 0xffff0000, v146
	v_lshl_add_u64 v[2:3], v[2:3], 0, v[154:155]
	v_pk_mul_f32 v[12:13], v[14:15], v[12:13]
	v_cvt_f32_f16_e32 v14, v5
	v_cvt_f32_f16_sdwa v15, v5 dst_sel:DWORD dst_unused:UNUSED_PAD src0_sel:WORD_1
	v_cvt_pk_bf16_f32 v4, v12, v13
	v_lshlrev_b32_e32 v12, 16, v147
	v_and_b32_e32 v13, 0xffff0000, v147
	v_pk_mul_f32 v[12:13], v[12:13], v[14:15]
	v_cvt_f32_f16_e32 v14, v6
	v_cvt_f32_f16_sdwa v15, v6 dst_sel:DWORD dst_unused:UNUSED_PAD src0_sel:WORD_1
	v_cvt_pk_bf16_f32 v5, v12, v13
	v_lshlrev_b32_e32 v12, 16, v148
	v_and_b32_e32 v13, 0xffff0000, v148
	v_pk_mul_f32 v[12:13], v[12:13], v[14:15]
	v_cvt_f32_f16_e32 v14, v7
	v_cvt_f32_f16_sdwa v15, v7 dst_sel:DWORD dst_unused:UNUSED_PAD src0_sel:WORD_1
	v_cvt_pk_bf16_f32 v6, v12, v13
	v_lshlrev_b32_e32 v12, 16, v149
	v_and_b32_e32 v13, 0xffff0000, v149
	v_pk_mul_f32 v[12:13], v[12:13], v[14:15]
	v_add_co_u32_e32 v16, vcc, s16, v2
	v_cvt_pk_bf16_f32 v7, v12, v13
	global_store_dwordx4 v[2:3], v[4:7], off
	s_waitcnt lgkmcnt(0)
	v_cvt_f32_f16_e32 v12, v8
	v_cvt_f32_f16_sdwa v13, v8 dst_sel:DWORD dst_unused:UNUSED_PAD src0_sel:WORD_1
	v_cvt_f32_f16_e32 v6, v9
	v_cvt_f32_f16_sdwa v7, v9 dst_sel:DWORD dst_unused:UNUSED_PAD src0_sel:WORD_1
	s_waitcnt vmcnt(1)
	v_lshlrev_b32_e32 v8, 16, v151
	v_and_b32_e32 v9, 0xffff0000, v151
	v_lshlrev_b32_e32 v4, 16, v150
	v_pk_mul_f32 v[6:7], v[8:9], v[6:7]
	v_cvt_f32_f16_e32 v8, v10
	v_cvt_f32_f16_sdwa v9, v10 dst_sel:DWORD dst_unused:UNUSED_PAD src0_sel:WORD_1
	v_and_b32_e32 v5, 0xffff0000, v150
	v_pk_mul_f32 v[4:5], v[4:5], v[12:13]
	v_lshlrev_b32_e32 v10, 16, v153
	v_cvt_pk_bf16_f32 v4, v4, v5
	v_cvt_pk_bf16_f32 v5, v6, v7
	v_lshlrev_b32_e32 v6, 16, v152
	v_and_b32_e32 v7, 0xffff0000, v152
	v_pk_mul_f32 v[6:7], v[6:7], v[8:9]
	v_cvt_f32_f16_e32 v8, v11
	v_cvt_f32_f16_sdwa v9, v11 dst_sel:DWORD dst_unused:UNUSED_PAD src0_sel:WORD_1
	v_and_b32_e32 v11, 0xffff0000, v153
	v_cvt_pk_bf16_f32 v6, v6, v7
	v_addc_co_u32_e32 v17, vcc, 0, v3, vcc
	v_pk_mul_f32 v[8:9], v[10:11], v[8:9]
	ds_read_b128 v[12:15], v1 offset:52416
	v_cvt_pk_bf16_f32 v7, v8, v9
	ds_read_b128 v[8:11], v1 offset:51328
	global_store_dwordx4 v[16:17], v[4:7], off
	s_waitcnt lgkmcnt(0)
	v_cvt_f32_f16_e32 v18, v8
	v_cvt_f32_f16_e32 v6, v9
	v_cvt_f32_f16_sdwa v7, v9 dst_sel:DWORD dst_unused:UNUSED_PAD src0_sel:WORD_1
	v_cvt_f32_f16_sdwa v19, v8 dst_sel:DWORD dst_unused:UNUSED_PAD src0_sel:WORD_1
	s_waitcnt vmcnt(2)
	v_lshlrev_b32_e32 v8, 16, v55
	v_and_b32_e32 v9, 0xffff0000, v55
	v_pk_mul_f32 v[6:7], v[8:9], v[6:7]
	v_cvt_f32_f16_e32 v8, v10
	v_cvt_f32_f16_sdwa v9, v10 dst_sel:DWORD dst_unused:UNUSED_PAD src0_sel:WORD_1
	v_lshlrev_b32_e32 v4, 16, v54
	v_and_b32_e32 v5, 0xffff0000, v54
	v_pk_mul_f32 v[4:5], v[4:5], v[18:19]
	v_lshlrev_b32_e32 v10, 16, v57
	v_cvt_pk_bf16_f32 v4, v4, v5
	v_cvt_pk_bf16_f32 v5, v6, v7
	v_lshlrev_b32_e32 v6, 16, v56
	v_and_b32_e32 v7, 0xffff0000, v56
	v_pk_mul_f32 v[6:7], v[6:7], v[8:9]
	v_cvt_f32_f16_e32 v8, v11
	v_cvt_f32_f16_sdwa v9, v11 dst_sel:DWORD dst_unused:UNUSED_PAD src0_sel:WORD_1
	v_and_b32_e32 v11, 0xffff0000, v57
	v_cvt_pk_bf16_f32 v6, v6, v7
	v_pk_mul_f32 v[8:9], v[10:11], v[8:9]
	s_nop 0
	v_cvt_pk_bf16_f32 v7, v8, v9
	v_add_co_u32_e32 v8, vcc, s41, v2
	v_cvt_f32_f16_e32 v10, v12
	s_nop 0
	v_addc_co_u32_e32 v9, vcc, 0, v3, vcc
	global_store_dwordx4 v[8:9], v[4:7], off
	v_cvt_f32_f16_sdwa v11, v12 dst_sel:DWORD dst_unused:UNUSED_PAD src0_sel:WORD_1
	s_waitcnt vmcnt(3)
	v_lshlrev_b32_e32 v8, 16, v51
	v_cvt_f32_f16_e32 v6, v13
	v_cvt_f32_f16_sdwa v7, v13 dst_sel:DWORD dst_unused:UNUSED_PAD src0_sel:WORD_1
	v_and_b32_e32 v9, 0xffff0000, v51
	v_lshlrev_b32_e32 v4, 16, v50
	v_and_b32_e32 v5, 0xffff0000, v50
	v_pk_mul_f32 v[6:7], v[8:9], v[6:7]
	v_cvt_f32_f16_e32 v8, v14
	v_cvt_f32_f16_sdwa v9, v14 dst_sel:DWORD dst_unused:UNUSED_PAD src0_sel:WORD_1
	v_pk_mul_f32 v[4:5], v[4:5], v[10:11]
	v_lshlrev_b32_e32 v10, 16, v53
	v_cvt_pk_bf16_f32 v4, v4, v5
	v_cvt_pk_bf16_f32 v5, v6, v7
	v_lshlrev_b32_e32 v6, 16, v52
	v_and_b32_e32 v7, 0xffff0000, v52
	v_pk_mul_f32 v[6:7], v[6:7], v[8:9]
	v_cvt_f32_f16_e32 v8, v15
	v_cvt_f32_f16_sdwa v9, v15 dst_sel:DWORD dst_unused:UNUSED_PAD src0_sel:WORD_1
	v_and_b32_e32 v11, 0xffff0000, v53
	v_cvt_pk_bf16_f32 v6, v6, v7
	v_add_co_u32_e32 v16, vcc, s50, v2
	v_pk_mul_f32 v[8:9], v[10:11], v[8:9]
	s_nop 0
	v_addc_co_u32_e32 v17, vcc, 0, v3, vcc
	v_cvt_pk_bf16_f32 v7, v8, v9
	ds_read_b128 v[8:11], v1 offset:53504
	ds_read_b128 v[12:15], v1 offset:54592
	global_store_dwordx4 v[16:17], v[4:7], off
	s_waitcnt lgkmcnt(1)
	v_cvt_f32_f16_e32 v18, v8
	v_cvt_f32_f16_e32 v6, v9
	v_cvt_f32_f16_sdwa v7, v9 dst_sel:DWORD dst_unused:UNUSED_PAD src0_sel:WORD_1
	v_cvt_f32_f16_sdwa v19, v8 dst_sel:DWORD dst_unused:UNUSED_PAD src0_sel:WORD_1
	s_waitcnt vmcnt(4)
	v_lshlrev_b32_e32 v8, 16, v47
	v_and_b32_e32 v9, 0xffff0000, v47
	v_pk_mul_f32 v[6:7], v[8:9], v[6:7]
	v_cvt_f32_f16_e32 v8, v10
	v_cvt_f32_f16_sdwa v9, v10 dst_sel:DWORD dst_unused:UNUSED_PAD src0_sel:WORD_1
	v_lshlrev_b32_e32 v4, 16, v46
	v_and_b32_e32 v5, 0xffff0000, v46
	v_pk_mul_f32 v[4:5], v[4:5], v[18:19]
	v_lshlrev_b32_e32 v10, 16, v49
	v_cvt_pk_bf16_f32 v4, v4, v5
	v_cvt_pk_bf16_f32 v5, v6, v7
	v_lshlrev_b32_e32 v6, 16, v48
	v_and_b32_e32 v7, 0xffff0000, v48
	v_pk_mul_f32 v[6:7], v[6:7], v[8:9]
	v_cvt_f32_f16_e32 v8, v11
	v_cvt_f32_f16_sdwa v9, v11 dst_sel:DWORD dst_unused:UNUSED_PAD src0_sel:WORD_1
	v_and_b32_e32 v11, 0xffff0000, v49
	v_cvt_pk_bf16_f32 v6, v6, v7
	v_pk_mul_f32 v[8:9], v[10:11], v[8:9]
	s_nop 0
	v_cvt_pk_bf16_f32 v7, v8, v9
	v_add_co_u32_e32 v8, vcc, s51, v2
	s_waitcnt lgkmcnt(0)
	v_cvt_f32_f16_e32 v10, v12
	v_addc_co_u32_e32 v9, vcc, 0, v3, vcc
	global_store_dwordx4 v[8:9], v[4:7], off
	v_cvt_f32_f16_sdwa v11, v12 dst_sel:DWORD dst_unused:UNUSED_PAD src0_sel:WORD_1
	s_waitcnt vmcnt(5)
	v_lshlrev_b32_e32 v8, 16, v43
	v_cvt_f32_f16_e32 v6, v13
	v_cvt_f32_f16_sdwa v7, v13 dst_sel:DWORD dst_unused:UNUSED_PAD src0_sel:WORD_1
	v_and_b32_e32 v9, 0xffff0000, v43
	v_lshlrev_b32_e32 v4, 16, v42
	v_and_b32_e32 v5, 0xffff0000, v42
	v_pk_mul_f32 v[6:7], v[8:9], v[6:7]
	v_cvt_f32_f16_e32 v8, v14
	v_cvt_f32_f16_sdwa v9, v14 dst_sel:DWORD dst_unused:UNUSED_PAD src0_sel:WORD_1
	v_pk_mul_f32 v[4:5], v[4:5], v[10:11]
	v_lshlrev_b32_e32 v10, 16, v45
	v_cvt_pk_bf16_f32 v4, v4, v5
	v_cvt_pk_bf16_f32 v5, v6, v7
	v_lshlrev_b32_e32 v6, 16, v44
	v_and_b32_e32 v7, 0xffff0000, v44
	v_pk_mul_f32 v[6:7], v[6:7], v[8:9]
	v_cvt_f32_f16_e32 v8, v15
	v_cvt_f32_f16_sdwa v9, v15 dst_sel:DWORD dst_unused:UNUSED_PAD src0_sel:WORD_1
	v_and_b32_e32 v11, 0xffff0000, v45
	v_cvt_pk_bf16_f32 v6, v6, v7
	v_add_co_u32_e32 v16, vcc, s52, v2
	v_pk_mul_f32 v[8:9], v[10:11], v[8:9]
	s_nop 0
	v_addc_co_u32_e32 v17, vcc, 0, v3, vcc
	v_cvt_pk_bf16_f32 v7, v8, v9
	ds_read_b128 v[8:11], v1 offset:55680
	ds_read_b128 v[12:15], v1 offset:56768
	global_store_dwordx4 v[16:17], v[4:7], off
	s_waitcnt lgkmcnt(1)
	v_cvt_f32_f16_e32 v18, v8
	v_cvt_f32_f16_e32 v6, v9
	v_cvt_f32_f16_sdwa v7, v9 dst_sel:DWORD dst_unused:UNUSED_PAD src0_sel:WORD_1
	v_cvt_f32_f16_sdwa v19, v8 dst_sel:DWORD dst_unused:UNUSED_PAD src0_sel:WORD_1
	s_waitcnt vmcnt(6)
	v_lshlrev_b32_e32 v8, 16, v39
	v_and_b32_e32 v9, 0xffff0000, v39
	v_pk_mul_f32 v[6:7], v[8:9], v[6:7]
	v_cvt_f32_f16_e32 v8, v10
	v_cvt_f32_f16_sdwa v9, v10 dst_sel:DWORD dst_unused:UNUSED_PAD src0_sel:WORD_1
	v_lshlrev_b32_e32 v4, 16, v38
	v_and_b32_e32 v5, 0xffff0000, v38
	v_pk_mul_f32 v[4:5], v[4:5], v[18:19]
	v_lshlrev_b32_e32 v10, 16, v41
	v_cvt_pk_bf16_f32 v4, v4, v5
	v_cvt_pk_bf16_f32 v5, v6, v7
	v_lshlrev_b32_e32 v6, 16, v40
	v_and_b32_e32 v7, 0xffff0000, v40
	v_pk_mul_f32 v[6:7], v[6:7], v[8:9]
	v_cvt_f32_f16_e32 v8, v11
	v_cvt_f32_f16_sdwa v9, v11 dst_sel:DWORD dst_unused:UNUSED_PAD src0_sel:WORD_1
	v_and_b32_e32 v11, 0xffff0000, v41
	v_cvt_pk_bf16_f32 v6, v6, v7
	v_pk_mul_f32 v[8:9], v[10:11], v[8:9]
	s_nop 0
	v_cvt_pk_bf16_f32 v7, v8, v9
	v_add_co_u32_e32 v8, vcc, s53, v2
	s_waitcnt lgkmcnt(0)
	v_cvt_f32_f16_e32 v10, v12
	v_addc_co_u32_e32 v9, vcc, 0, v3, vcc
	global_store_dwordx4 v[8:9], v[4:7], off
	v_cvt_f32_f16_sdwa v11, v12 dst_sel:DWORD dst_unused:UNUSED_PAD src0_sel:WORD_1
	s_waitcnt vmcnt(7)
	v_lshlrev_b32_e32 v8, 16, v35
	v_cvt_f32_f16_e32 v6, v13
	v_cvt_f32_f16_sdwa v7, v13 dst_sel:DWORD dst_unused:UNUSED_PAD src0_sel:WORD_1
	v_and_b32_e32 v9, 0xffff0000, v35
	v_lshlrev_b32_e32 v4, 16, v34
	v_and_b32_e32 v5, 0xffff0000, v34
	v_pk_mul_f32 v[6:7], v[8:9], v[6:7]
	v_cvt_f32_f16_e32 v8, v14
	v_cvt_f32_f16_sdwa v9, v14 dst_sel:DWORD dst_unused:UNUSED_PAD src0_sel:WORD_1
	v_pk_mul_f32 v[4:5], v[4:5], v[10:11]
	v_lshlrev_b32_e32 v10, 16, v37
	v_cvt_pk_bf16_f32 v4, v4, v5
	v_cvt_pk_bf16_f32 v5, v6, v7
	v_lshlrev_b32_e32 v6, 16, v36
	v_and_b32_e32 v7, 0xffff0000, v36
	v_pk_mul_f32 v[6:7], v[6:7], v[8:9]
	v_cvt_f32_f16_e32 v8, v15
	v_cvt_f32_f16_sdwa v9, v15 dst_sel:DWORD dst_unused:UNUSED_PAD src0_sel:WORD_1
	v_and_b32_e32 v11, 0xffff0000, v37
	v_add_co_u32_e32 v2, vcc, 0x1c000, v2
	v_pk_mul_f32 v[8:9], v[10:11], v[8:9]
	v_cvt_pk_bf16_f32 v6, v6, v7
	v_cvt_pk_bf16_f32 v7, v8, v9
	v_addc_co_u32_e32 v3, vcc, 0, v3, vcc
	global_store_dwordx4 v[2:3], v[4:7], off
